# barrier leader exit: drop unused XGEN bump and its two vmcnt(0) waits
# speedup vs baseline: 1.0069x; 1.0002x over previous
; __device__ __forceinline__ unsigned xb_ld(unsigned* p)              { return __hip_atomic_load(p, __ATOMIC_RELAXED, __HIP_MEMORY_SCOPE_AGENT); }
; __device__ __forceinline__ unsigned xb_add(unsigned* p, unsigned v) { return __hip_atomic_fetch_add(p, v, __ATOMIC_RELAXED, __HIP_MEMORY_SCOPE_AGENT); }
; #define XB_SPIN(cond, bar) do { unsigned _sp = 0; while (cond) { __builtin_amdgcn_s_sleep(1); \
;     if ((++_sp & 255u) == 0u) { if (xb_ld(&(bar)[XB_TMO])) break; if (_sp > XB_SPIN_CAP) { atomicAdd(&(bar)[XB_TMO], 1u); break; } } } } while (0)
; __device__ __forceinline__ void xcd_barrier(const XcdBarrier& b, int wv) {
;     ...
;             if (og + 1u == (tg + 1u) * nx) xb_add(&bar[XB_TOPGEN], 1u);
;             else XB_SPIN(xb_ld(&bar[XB_TOPGEN]) == tg, bar);
;             __builtin_amdgcn_fence(__ATOMIC_ACQUIRE, "agent");
;             xb_add(&bar[XB_XGEN(bx)], 1u);
;             asm volatile("s_waitcnt vmcnt(0)" ::: "memory");
.LBB0_173:
	s_or_b64 exec, exec, s[4:5]
	s_mov_b64 s[4:5], exec
	v_mbcnt_lo_u32_b32 v0, s4, 0
	v_mbcnt_hi_u32_b32 v0, s5, v0
	s_mov_b32 s9, 0
	v_cmp_eq_u32_e32 vcc, 0, v0
	s_nop 0
	s_and_saveexec_b64 s[6:7], vcc
	s_cbranch_execz .LBB0_175
	s_add_i32 s8, s3, 0x900
	s_lshl_b64 s[8:9], s[8:9], 2
	s_add_u32 s8, s82, s8
	s_addc_u32 s9, s83, s9
	s_bcnt1_i32_b64 s3, s[4:5]
	v_mov_b32_e32 v0, 0
	v_mov_b32_e32 v1, s3
.LBB0_175:
	s_or_b64 exec, exec, s[6:7]
	s_nop 0

; __device__ __forceinline__ unsigned xb_ld(unsigned* p)              { return __hip_atomic_load(p, __ATOMIC_RELAXED, __HIP_MEMORY_SCOPE_AGENT); }
; __device__ __forceinline__ unsigned xb_add(unsigned* p, unsigned v) { return __hip_atomic_fetch_add(p, v, __ATOMIC_RELAXED, __HIP_MEMORY_SCOPE_AGENT); }
; #define XB_SPIN(cond, bar) do { unsigned _sp = 0; while (cond) { __builtin_amdgcn_s_sleep(1); \
;     if ((++_sp & 255u) == 0u) { if (xb_ld(&(bar)[XB_TMO])) break; if (_sp > XB_SPIN_CAP) { atomicAdd(&(bar)[XB_TMO], 1u); break; } } } } while (0)
; __device__ __forceinline__ void xcd_barrier(const XcdBarrier& b, int wv) {
;     ...
;             if (og + 1u == (tg + 1u) * nx) xb_add(&bar[XB_TOPGEN], 1u);
;             else XB_SPIN(xb_ld(&bar[XB_TOPGEN]) == tg, bar);
;             __builtin_amdgcn_fence(__ATOMIC_ACQUIRE, "agent");
;             xb_add(&bar[XB_XGEN(bx)], 1u);
;             asm volatile("s_waitcnt vmcnt(0)" ::: "memory");
.LBB0_274:
	s_or_b64 exec, exec, s[10:11]
	s_mov_b64 s[10:11], exec
	v_mbcnt_lo_u32_b32 v1, s10, 0
	v_mbcnt_hi_u32_b32 v1, s11, v1
	v_cmp_eq_u32_e32 vcc, 0, v1
	s_nop 0
	s_and_saveexec_b64 s[14:15], vcc
	s_cbranch_execz .LBB0_276
	s_add_i32 s36, s42, 0x900
	s_lshl_b64 s[16:17], s[36:37], 2
	s_add_u32 s16, s82, s16
	s_addc_u32 s17, s83, s17
	s_bcnt1_i32_b64 s10, s[10:11]
	v_mov_b32_e32 v1, s10
.LBB0_276:
	s_or_b64 exec, exec, s[14:15]
	s_nop 0

; __device__ __forceinline__ unsigned xb_ld(unsigned* p)              { return __hip_atomic_load(p, __ATOMIC_RELAXED, __HIP_MEMORY_SCOPE_AGENT); }
; __device__ __forceinline__ unsigned xb_add(unsigned* p, unsigned v) { return __hip_atomic_fetch_add(p, v, __ATOMIC_RELAXED, __HIP_MEMORY_SCOPE_AGENT); }
; #define XB_SPIN(cond, bar) do { unsigned _sp = 0; while (cond) { __builtin_amdgcn_s_sleep(1); \
;     if ((++_sp & 255u) == 0u) { if (xb_ld(&(bar)[XB_TMO])) break; if (_sp > XB_SPIN_CAP) { atomicAdd(&(bar)[XB_TMO], 1u); break; } } } } while (0)
; __device__ __forceinline__ void xcd_barrier(const XcdBarrier& b, int wv) {
;     ...
;             if (og + 1u == (tg + 1u) * nx) xb_add(&bar[XB_TOPGEN], 1u);
;             else XB_SPIN(xb_ld(&bar[XB_TOPGEN]) == tg, bar);
;             __builtin_amdgcn_fence(__ATOMIC_ACQUIRE, "agent");
;             xb_add(&bar[XB_XGEN(bx)], 1u);
;             asm volatile("s_waitcnt vmcnt(0)" ::: "memory");
.LBB0_382:
	s_or_b64 exec, exec, s[6:7]
	s_mov_b64 s[6:7], exec
	v_mbcnt_lo_u32_b32 v1, s6, 0
	v_mbcnt_hi_u32_b32 v1, s7, v1
	v_cmp_eq_u32_e32 vcc, 0, v1
	s_nop 0
	s_and_saveexec_b64 s[10:11], vcc
	s_cbranch_execz .LBB0_384
	s_add_i32 s36, s42, 0x900
	s_lshl_b64 s[14:15], s[36:37], 2
	s_add_u32 s14, s82, s14
	s_addc_u32 s15, s83, s15
	s_bcnt1_i32_b64 s6, s[6:7]
	v_mov_b32_e32 v1, s6
.LBB0_384:
	s_or_b64 exec, exec, s[10:11]
	s_nop 0

; __device__ __forceinline__ unsigned xb_ld(unsigned* p)              { return __hip_atomic_load(p, __ATOMIC_RELAXED, __HIP_MEMORY_SCOPE_AGENT); }
; __device__ __forceinline__ unsigned xb_add(unsigned* p, unsigned v) { return __hip_atomic_fetch_add(p, v, __ATOMIC_RELAXED, __HIP_MEMORY_SCOPE_AGENT); }
; #define XB_SPIN(cond, bar) do { unsigned _sp = 0; while (cond) { __builtin_amdgcn_s_sleep(1); \
;     if ((++_sp & 255u) == 0u) { if (xb_ld(&(bar)[XB_TMO])) break; if (_sp > XB_SPIN_CAP) { atomicAdd(&(bar)[XB_TMO], 1u); break; } } } } while (0)
; __device__ __forceinline__ void xcd_barrier(const XcdBarrier& b, int wv) {
;     ...
;             if (og + 1u == (tg + 1u) * nx) xb_add(&bar[XB_TOPGEN], 1u);
;             else XB_SPIN(xb_ld(&bar[XB_TOPGEN]) == tg, bar);
;             __builtin_amdgcn_fence(__ATOMIC_ACQUIRE, "agent");
;             xb_add(&bar[XB_XGEN(bx)], 1u);
;             asm volatile("s_waitcnt vmcnt(0)" ::: "memory");
.LBB0_556:
	s_or_b64 exec, exec, s[4:5]
	s_mov_b64 s[4:5], exec
	v_mbcnt_lo_u32_b32 v1, s4, 0
	v_mbcnt_hi_u32_b32 v1, s5, v1
	v_cmp_eq_u32_e32 vcc, 0, v1
	s_nop 0
	s_and_saveexec_b64 s[6:7], vcc
	s_cbranch_execz .LBB0_558
	s_add_i32 s36, s42, 0x900
	s_lshl_b64 s[8:9], s[36:37], 2
	s_add_u32 s8, s82, s8
	s_addc_u32 s9, s83, s9
	s_bcnt1_i32_b64 s4, s[4:5]
	v_mov_b32_e32 v1, s4

; __device__ __forceinline__ unsigned xb_ld(unsigned* p)              { return __hip_atomic_load(p, __ATOMIC_RELAXED, __HIP_MEMORY_SCOPE_AGENT); }
; __device__ __forceinline__ unsigned xb_add(unsigned* p, unsigned v) { return __hip_atomic_fetch_add(p, v, __ATOMIC_RELAXED, __HIP_MEMORY_SCOPE_AGENT); }
; #define XB_SPIN(cond, bar) do { unsigned _sp = 0; while (cond) { __builtin_amdgcn_s_sleep(1); \
;     if ((++_sp & 255u) == 0u) { if (xb_ld(&(bar)[XB_TMO])) break; if (_sp > XB_SPIN_CAP) { atomicAdd(&(bar)[XB_TMO], 1u); break; } } } } while (0)
; __device__ __forceinline__ void xcd_barrier(const XcdBarrier& b, int wv) {
;     ...
;             if (og + 1u == (tg + 1u) * nx) xb_add(&bar[XB_TOPGEN], 1u);
;             else XB_SPIN(xb_ld(&bar[XB_TOPGEN]) == tg, bar);
;             __builtin_amdgcn_fence(__ATOMIC_ACQUIRE, "agent");
;             xb_add(&bar[XB_XGEN(bx)], 1u);
;             asm volatile("s_waitcnt vmcnt(0)" ::: "memory");
.LBB0_795:
	s_or_b64 exec, exec, s[4:5]
	s_mov_b64 s[4:5], exec
	v_mbcnt_lo_u32_b32 v1, s4, 0
	v_mbcnt_hi_u32_b32 v1, s5, v1
	v_cmp_eq_u32_e32 vcc, 0, v1
	s_nop 0
	s_and_saveexec_b64 s[6:7], vcc
	s_cbranch_execz .LBB0_444
	s_add_i32 s36, s42, 0x900
	s_lshl_b64 s[8:9], s[36:37], 2
	s_add_u32 s8, s82, s8
	s_addc_u32 s9, s83, s9
	s_bcnt1_i32_b64 s4, s[4:5]
	v_mov_b32_e32 v1, s4
	s_branch .LBB0_444

; __device__ __forceinline__ unsigned xb_ld(unsigned* p)              { return __hip_atomic_load(p, __ATOMIC_RELAXED, __HIP_MEMORY_SCOPE_AGENT); }
; __device__ __forceinline__ unsigned xb_add(unsigned* p, unsigned v) { return __hip_atomic_fetch_add(p, v, __ATOMIC_RELAXED, __HIP_MEMORY_SCOPE_AGENT); }
; #define XB_SPIN(cond, bar) do { unsigned _sp = 0; while (cond) { __builtin_amdgcn_s_sleep(1); \
;     if ((++_sp & 255u) == 0u) { if (xb_ld(&(bar)[XB_TMO])) break; if (_sp > XB_SPIN_CAP) { atomicAdd(&(bar)[XB_TMO], 1u); break; } } } } while (0)
; __device__ __forceinline__ void xcd_barrier(const XcdBarrier& b, int wv) {
;     ...
;             if (og + 1u == (tg + 1u) * nx) xb_add(&bar[XB_TOPGEN], 1u);
;             else XB_SPIN(xb_ld(&bar[XB_TOPGEN]) == tg, bar);
;             __builtin_amdgcn_fence(__ATOMIC_ACQUIRE, "agent");
;             xb_add(&bar[XB_XGEN(bx)], 1u);
;             asm volatile("s_waitcnt vmcnt(0)" ::: "memory");
.LBB0_849:
	s_or_b64 exec, exec, s[8:9]
	s_mov_b64 s[8:9], exec
	v_mbcnt_lo_u32_b32 v4, s8, 0
	v_mbcnt_hi_u32_b32 v4, s9, v4
	s_mov_b32 s13, 0
	v_cmp_eq_u32_e32 vcc, 0, v4
	s_nop 0
	s_and_saveexec_b64 s[10:11], vcc
	s_cbranch_execz .LBB0_851
	s_add_i32 s12, s24, 0x900
	s_lshl_b64 s[12:13], s[12:13], 2
	s_add_u32 s12, s82, s12
	s_addc_u32 s13, s83, s13
	s_bcnt1_i32_b64 s8, s[8:9]
	v_mov_b32_e32 v4, 0
	v_mov_b32_e32 v5, s8
